# plus hand-scheduled rmsnorm row loop of the norm+k_pe phase (gains loaded once, 8 row loads in flight)
# speedup vs baseline: 1.0241x; 1.0027x over previous
.LBB2_716:
	v_ashrrev_i32_e32 v55, 31, v54
	v_lshlrev_b64 v[2:3], 12, v[54:55]
	v_lshl_add_u64 v[62:63], v[52:53], 0, v[2:3]
	v_lshlrev_b64 v[2:3], 13, v[54:55]
	v_lshl_add_u64 v[64:65], v[56:57], 0, v[2:3]
	s_mov_b64 s[0:1], 0
	v_mov_b32_e32 v55, v75
	global_load_dwordx4 v[88:91], v[38:39], off
	global_load_dwordx4 v[92:95], v[38:39], off offset:1024
	global_load_dwordx4 v[96:99], v[38:39], off offset:2048
	global_load_dwordx4 v[100:103], v[38:39], off offset:3072
	global_load_dwordx4 v[104:107], v[40:41], off
	global_load_dwordx4 v[108:111], v[42:43], off
	global_load_dwordx4 v[112:115], v[44:45], off
	global_load_dwordx4 v[116:119], v[46:47], off
.Lnk_loop:
	global_load_dwordx4 v[156:159], v[64:65], off offset:-4096
	global_load_dwordx4 v[160:163], v[64:65], off offset:-3072
	global_load_dwordx4 v[164:167], v[64:65], off offset:-2048
	global_load_dwordx4 v[168:171], v[64:65], off offset:-1024
	global_load_dwordx4 v[172:175], v[64:65], off
	global_load_dwordx4 v[176:179], v[64:65], off offset:1024
	global_load_dwordx4 v[180:183], v[64:65], off offset:2048
	global_load_dwordx4 v[184:187], v[64:65], off offset:3072
	s_mov_b32 s3, 0x1800000
	s_mov_b64 s[4:5], 0x2000
	v_lshl_add_u64 v[30:31], v[62:63], 0, s[0:1]
	v_lshl_add_u64 v[64:65], v[64:65], 0, s[4:5]
	v_add_co_u32_e32 v30, vcc, s3, v30
	s_nop 1
	v_addc_co_u32_e32 v31, vcc, 0, v31, vcc
	s_waitcnt vmcnt(0)
	v_mul_f32_e32 v2, v156, v156
	v_mul_f32_e32 v3, v158, v158
	v_fmac_f32_e32 v2, v157, v157
	v_fmac_f32_e32 v3, v159, v159
	v_add_f32_e32 v0, v2, v3
	v_mul_f32_e32 v2, v160, v160
	v_mul_f32_e32 v3, v162, v162
	v_fmac_f32_e32 v2, v161, v161
	v_fmac_f32_e32 v3, v163, v163
	v_add_f32_e32 v2, v2, v3
	v_add_f32_e32 v0, v0, v2
	v_mul_f32_e32 v2, v164, v164
	v_mul_f32_e32 v3, v166, v166
	v_fmac_f32_e32 v2, v165, v165
	v_fmac_f32_e32 v3, v167, v167
	v_add_f32_e32 v2, v2, v3
	v_add_f32_e32 v0, v0, v2
	v_mul_f32_e32 v2, v168, v168
	v_mul_f32_e32 v3, v170, v170
	v_fmac_f32_e32 v2, v169, v169
	v_fmac_f32_e32 v3, v171, v171
	v_add_f32_e32 v2, v2, v3
	v_add_f32_e32 v0, v0, v2
	v_mul_f32_e32 v2, v172, v172
	v_mul_f32_e32 v3, v174, v174
	v_fmac_f32_e32 v2, v173, v173
	v_fmac_f32_e32 v3, v175, v175
	v_add_f32_e32 v2, v2, v3
	v_add_f32_e32 v0, v0, v2
	v_mul_f32_e32 v2, v176, v176
	v_mul_f32_e32 v3, v178, v178
	v_fmac_f32_e32 v2, v177, v177
	v_fmac_f32_e32 v3, v179, v179
	v_add_f32_e32 v2, v2, v3
	v_add_f32_e32 v0, v0, v2
	v_mul_f32_e32 v2, v180, v180
	v_mul_f32_e32 v3, v182, v182
	v_fmac_f32_e32 v2, v181, v181
	v_fmac_f32_e32 v3, v183, v183
	v_add_f32_e32 v2, v2, v3
	v_add_f32_e32 v0, v0, v2
	v_mul_f32_e32 v2, v184, v184
	v_mul_f32_e32 v3, v186, v186
	v_fmac_f32_e32 v2, v185, v185
	v_fmac_f32_e32 v3, v187, v187
	v_add_f32_e32 v2, v2, v3
	v_add_f32_e32 v0, v0, v2
	ds_bpermute_b32 v78, v68, v0
	s_waitcnt lgkmcnt(0)
	v_add_f32_e32 v0, v0, v78
	ds_bpermute_b32 v78, v69, v0
	s_waitcnt lgkmcnt(0)
	v_add_f32_e32 v0, v0, v78
	ds_bpermute_b32 v78, v70, v0
	s_waitcnt lgkmcnt(0)
	v_add_f32_e32 v0, v0, v78
	ds_bpermute_b32 v78, v71, v0
	s_waitcnt lgkmcnt(0)
	v_add_f32_e32 v0, v0, v78
	ds_bpermute_b32 v78, v72, v0
	s_waitcnt lgkmcnt(0)
	v_add_f32_e32 v0, v0, v78
	ds_bpermute_b32 v78, v73, v0
	s_waitcnt lgkmcnt(0)
	v_add_f32_e32 v0, v0, v78
	v_fmamk_f32 v0, v0, 0x3a000000, v147
	v_cmp_gt_f32_e32 vcc, s29, v0
	v_mul_f32_e32 v78, 0x4b800000, v0
	s_nop 0
	v_cndmask_b32_e32 v0, v0, v78, vcc
	v_rsq_f32_e32 v0, v0
	s_nop 0
	v_mul_f32_e32 v78, 0x45800000, v0
	v_cndmask_b32_e32 v0, v0, v78, vcc
	v_mul_f32_e32 v2, v156, v0
	v_mul_f32_e32 v3, v157, v0
	v_mul_f32_e32 v4, v158, v0
	v_mul_f32_e32 v5, v159, v0
	v_mul_f32_e32 v2, v2, v88
	v_mul_f32_e32 v3, v3, v89
	v_mul_f32_e32 v4, v4, v90
	v_mul_f32_e32 v5, v5, v91
	v_cvt_pk_bf16_f32 v192, v2, v3
	v_cvt_pk_bf16_f32 v193, v4, v5
	global_store_dwordx2 v[30:31], v[192:193], off
	ds_write_b64 v55, v[192:193]
	v_mul_f32_e32 v2, v160, v0
	v_mul_f32_e32 v3, v161, v0
	v_mul_f32_e32 v4, v162, v0
	v_mul_f32_e32 v5, v163, v0
	v_mul_f32_e32 v2, v2, v92
	v_mul_f32_e32 v3, v3, v93
	v_mul_f32_e32 v4, v4, v94
	v_mul_f32_e32 v5, v5, v95
	v_cvt_pk_bf16_f32 v194, v2, v3
	v_cvt_pk_bf16_f32 v195, v4, v5
	global_store_dwordx2 v[30:31], v[194:195], off offset:512
	ds_write_b64 v55, v[194:195] offset:512
	v_mul_f32_e32 v2, v164, v0
	v_mul_f32_e32 v3, v165, v0
	v_mul_f32_e32 v4, v166, v0
	v_mul_f32_e32 v5, v167, v0
	v_mul_f32_e32 v2, v2, v96
	v_mul_f32_e32 v3, v3, v97
	v_mul_f32_e32 v4, v4, v98
	v_mul_f32_e32 v5, v5, v99
	v_cvt_pk_bf16_f32 v196, v2, v3
	v_cvt_pk_bf16_f32 v197, v4, v5
	global_store_dwordx2 v[30:31], v[196:197], off offset:1024
	ds_write_b64 v55, v[196:197] offset:1024
	v_mul_f32_e32 v2, v168, v0
	v_mul_f32_e32 v3, v169, v0
	v_mul_f32_e32 v4, v170, v0
	v_mul_f32_e32 v5, v171, v0
	v_mul_f32_e32 v2, v2, v100
	v_mul_f32_e32 v3, v3, v101
	v_mul_f32_e32 v4, v4, v102
	v_mul_f32_e32 v5, v5, v103
	v_cvt_pk_bf16_f32 v198, v2, v3
	v_cvt_pk_bf16_f32 v199, v4, v5
	global_store_dwordx2 v[30:31], v[198:199], off offset:1536
	ds_write_b64 v55, v[198:199] offset:1536
	v_mul_f32_e32 v2, v172, v0
	v_mul_f32_e32 v3, v173, v0
	v_mul_f32_e32 v4, v174, v0
	v_mul_f32_e32 v5, v175, v0
	v_mul_f32_e32 v2, v2, v104
	v_mul_f32_e32 v3, v3, v105
	v_mul_f32_e32 v4, v4, v106
	v_mul_f32_e32 v5, v5, v107
	v_cvt_pk_bf16_f32 v200, v2, v3
	v_cvt_pk_bf16_f32 v201, v4, v5
	global_store_dwordx2 v[30:31], v[200:201], off offset:2048
	ds_write_b64 v55, v[200:201] offset:2048
	v_mul_f32_e32 v2, v176, v0
	v_mul_f32_e32 v3, v177, v0
	v_mul_f32_e32 v4, v178, v0
	v_mul_f32_e32 v5, v179, v0
	v_mul_f32_e32 v2, v2, v108
	v_mul_f32_e32 v3, v3, v109
	v_mul_f32_e32 v4, v4, v110
	v_mul_f32_e32 v5, v5, v111
	v_cvt_pk_bf16_f32 v202, v2, v3
	v_cvt_pk_bf16_f32 v203, v4, v5
	global_store_dwordx2 v[30:31], v[202:203], off offset:2560
	ds_write_b64 v55, v[202:203] offset:2560
	v_mul_f32_e32 v2, v180, v0
	v_mul_f32_e32 v3, v181, v0
	v_mul_f32_e32 v4, v182, v0
	v_mul_f32_e32 v5, v183, v0
	v_mul_f32_e32 v2, v2, v112
	v_mul_f32_e32 v3, v3, v113
	v_mul_f32_e32 v4, v4, v114
	v_mul_f32_e32 v5, v5, v115
	v_cvt_pk_bf16_f32 v204, v2, v3
	v_cvt_pk_bf16_f32 v205, v4, v5
	global_store_dwordx2 v[30:31], v[204:205], off offset:3072
	ds_write_b64 v55, v[204:205] offset:3072
	v_mul_f32_e32 v2, v184, v0
	v_mul_f32_e32 v3, v185, v0
	v_mul_f32_e32 v4, v186, v0
	v_mul_f32_e32 v5, v187, v0
	v_mul_f32_e32 v2, v2, v116
	v_mul_f32_e32 v3, v3, v117
	v_mul_f32_e32 v4, v4, v118
	v_mul_f32_e32 v5, v5, v119
	v_cvt_pk_bf16_f32 v206, v2, v3
	v_cvt_pk_bf16_f32 v207, v4, v5
	global_store_dwordx2 v[30:31], v[206:207], off offset:3584
	ds_write_b64 v55, v[206:207] offset:3584
	s_add_u32 s0, s0, 0x1000
	s_addc_u32 s1, s1, 0
	v_add_u32_e32 v55, 0x1010, v55
	s_cmpk_eq_i32 s0, 0x4000
	s_cbranch_scc0 .Lnk_loop
	v_mov_b32_e32 v2, 0
	s_mov_b32 s0, 0
	v_mov_b64_e32 v[62:63], v[60:61]
	v_mov_b32_e32 v0, v76
	v_mov_b32_e32 v3, v2
	v_mov_b32_e32 v4, v2
	v_mov_b32_e32 v5, v2
	v_mov_b32_e32 v6, v2
	v_mov_b32_e32 v7, v2
	v_mov_b32_e32 v8, v2
	v_mov_b32_e32 v9, v2
	v_mov_b32_e32 v10, v2
	v_mov_b32_e32 v11, v2
	v_mov_b32_e32 v12, v2
	v_mov_b32_e32 v13, v2
	v_mov_b32_e32 v14, v2
	v_mov_b32_e32 v15, v2
	v_mov_b32_e32 v16, v2
	v_mov_b32_e32 v17, v2
	v_mov_b32_e32 v18, v2
	v_mov_b32_e32 v19, v2
	v_mov_b32_e32 v20, v2
	v_mov_b32_e32 v21, v2
	v_mov_b32_e32 v22, v2
	v_mov_b32_e32 v23, v2
	v_mov_b32_e32 v24, v2
	v_mov_b32_e32 v25, v2
	v_mov_b32_e32 v26, v2
	v_mov_b32_e32 v27, v2
	v_mov_b32_e32 v28, v2
	v_mov_b32_e32 v29, v2
	v_mov_b32_e32 v30, v2
	v_mov_b32_e32 v31, v2
	v_mov_b32_e32 v32, v2
	v_mov_b32_e32 v33, v2
	s_waitcnt lgkmcnt(0)
	s_barrier
